# attention tiles: the two halves of a workgroup take the same head in different batches (tile bits 0 and 8 swapped)
# speedup vs baseline: 1.0199x; 1.0006x over previous
.Lp2_na:
	s_mov_b64 exec, -1
	v_writelane_b32 v245, s0, 0
	v_writelane_b32 v245, s1, 1
	v_writelane_b32 v245, s2, 2
	v_writelane_b32 v245, s3, 3
	v_writelane_b32 v245, s4, 4
	v_writelane_b32 v245, s5, 5
	v_writelane_b32 v245, s6, 6
	v_writelane_b32 v245, s7, 7
	v_writelane_b32 v245, s8, 8
	v_writelane_b32 v245, s9, 9
	v_writelane_b32 v245, s10, 10
	v_writelane_b32 v245, s11, 11
	v_writelane_b32 v245, s12, 12
	v_writelane_b32 v245, s13, 13
	v_writelane_b32 v245, s14, 14
	v_writelane_b32 v245, s15, 15
	v_writelane_b32 v245, s16, 16
	v_writelane_b32 v245, s17, 17
	v_writelane_b32 v245, s18, 18
	v_writelane_b32 v245, s19, 19
	v_writelane_b32 v245, s20, 20
	v_writelane_b32 v245, s21, 21
	v_writelane_b32 v245, s22, 22
	v_writelane_b32 v245, s23, 23
	v_writelane_b32 v245, s24, 24
	v_writelane_b32 v245, s25, 25
	v_writelane_b32 v245, s26, 26
	v_writelane_b32 v245, s27, 27
	v_writelane_b32 v245, s28, 28
	v_writelane_b32 v245, s29, 29
	v_writelane_b32 v245, s30, 30
	v_writelane_b32 v245, s31, 31
	v_writelane_b32 v245, s32, 32
	v_writelane_b32 v245, s33, 33
	v_writelane_b32 v245, s34, 34
	v_writelane_b32 v245, s35, 35
	v_writelane_b32 v245, s36, 36
	v_writelane_b32 v245, s37, 37
	v_writelane_b32 v245, s38, 38
	v_writelane_b32 v245, s39, 39
	v_writelane_b32 v245, s40, 40
	v_writelane_b32 v245, s41, 41
	v_writelane_b32 v245, s42, 42
	v_writelane_b32 v245, s43, 43
	v_writelane_b32 v245, s44, 44
	v_writelane_b32 v245, s45, 45
	v_writelane_b32 v245, s46, 46
	v_writelane_b32 v245, s47, 47
	v_writelane_b32 v245, s48, 48
	v_writelane_b32 v245, s49, 49
	v_writelane_b32 v245, s50, 50
	v_writelane_b32 v245, s51, 51
	v_writelane_b32 v245, s52, 52
	v_writelane_b32 v245, s53, 53
	v_writelane_b32 v245, s54, 54
	v_writelane_b32 v245, s55, 55
	v_writelane_b32 v245, s56, 56
	v_writelane_b32 v245, s57, 57
	v_writelane_b32 v245, s58, 58
	v_writelane_b32 v245, s59, 59
	v_writelane_b32 v245, s60, 60
	v_writelane_b32 v245, s61, 61
	v_writelane_b32 v245, s62, 62
	v_writelane_b32 v245, s63, 63
	v_writelane_b32 v244, s64, 0
	v_writelane_b32 v244, s65, 1
	v_writelane_b32 v244, s66, 2
	v_writelane_b32 v244, s67, 3
	v_writelane_b32 v244, s68, 4
	v_writelane_b32 v244, s69, 5
	v_writelane_b32 v244, s70, 6
	v_writelane_b32 v244, s71, 7
	v_writelane_b32 v244, s72, 8
	v_writelane_b32 v244, s73, 9
	v_writelane_b32 v244, s74, 10
	v_writelane_b32 v244, s75, 11
	v_writelane_b32 v244, s76, 12
	v_writelane_b32 v244, s77, 13
	v_writelane_b32 v244, s78, 14
	v_writelane_b32 v244, s79, 15
	v_lshrrev_b32_e32 v235, 6, v225
	v_and_b32_e32 v246, 63, v225
	s_load_dwordx2 s[10:11], s[100:101], 0xb0
	s_load_dwordx2 s[12:13], s[100:101], 0x28
	v_readfirstlane_b32 s4, v235
	v_and_b32_e32 v236, 15, v246
	v_lshrrev_b32_e32 v237, 4, v246
	s_nop 3
	s_and_b32 s5, s4, 3
	s_lshr_b32 s6, s4, 2
	s_lshl_b32 s7, s99, 1
	s_add_u32 s7, s7, s6
	s_and_b32 s36, s7, 1
	s_bfe_u32 s37, s7, 0x10008
	s_andn2_b32 s7, s7, 0x101
	s_lshl_b32 s36, s36, 8
	s_or_b32 s7, s7, s36
	s_or_b32 s7, s7, s37
	s_lshl_b32 s8, s5, 4
	s_sub_i32 s8, s8, 8
	s_max_i32 s8, s8, 0
	s_min_i32 s8, s8, 32
	s_lshl_b32 s9, s5, 4
	v_lshrrev_b32_e32 v240, 2, v236
	v_and_b32_e32 v241, 3, v236
	v_lshl_add_u32 v240, v240, 3, v241
	v_lshlrev_b32_e32 v240, 10, v240
	v_lshl_add_u32 v218, v237, 4, v240
	v_add_u32_e32 v219, 0x1000, v218
	v_lshlrev_b32_e32 v240, 12, v236
	v_lshl_add_u32 v220, v237, 4, v240
	v_lshlrev_b32_e32 v240, 10, v236
	v_lshl_add_u32 v221, v237, 4, v240
	v_mul_u32_u24_e32 v240, 0xc00, v236
	v_lshl_add_u32 v222, v237, 3, v240
	v_xor_b32_e32 v223, 16, v246
	v_lshlrev_b32_e32 v223, 2, v223
	v_xor_b32_e32 v232, 32, v246
	v_lshlrev_b32_e32 v232, 2, v232
	s_lshr_b32 s36, s8, 3
	v_add_u32_e32 v136, s36, v237
	v_xor_b32_e32 v136, v136, v236
	v_lshlrev_b32_e32 v136, 4, v136
	v_lshl_or_b32 v136, v236, 10, v136
	s_lshl_b32 s36, s6, 16
	v_or_b32_e32 v136, s36, v136
	s_lshl_b32 s39, s5, 14
	s_add_u32 s39, s39, s36
	s_add_u32 s39, s39, 16
	v_add_u32_e32 v240, s9, v236
	v_lshl_add_u32 v241, v237, 3, s8
	v_sub_u32_e32 v235, v241, v240
	v_subrev_u32_e32 v240, 8, v240
	v_med3_i32 v240, v240, 0, 48
	v_sub_u32_e32 v241, v241, v240
	v_add_u32_e32 v240, 0, v235
	v_med3_i32 v240, v240, -15, 15
	v_add_u32_e32 v240, 15, v240
	v_lshlrev_b32_e32 v210, 2, v240
	v_add_u32_e32 v240, 0, v241
	v_cmp_gt_u32_e64 s[40:41], 16, v240
	v_add_u32_e32 v240, 1, v235
	v_med3_i32 v240, v240, -15, 15
	v_add_u32_e32 v240, 15, v240
	v_lshlrev_b32_e32 v211, 2, v240
	v_add_u32_e32 v240, 1, v241
	v_cmp_gt_u32_e64 s[42:43], 16, v240
	v_add_u32_e32 v240, 2, v235
	v_med3_i32 v240, v240, -15, 15
	v_add_u32_e32 v240, 15, v240
	v_lshlrev_b32_e32 v212, 2, v240
	v_add_u32_e32 v240, 2, v241
	v_cmp_gt_u32_e64 s[44:45], 16, v240
	v_add_u32_e32 v240, 3, v235
	v_med3_i32 v240, v240, -15, 15
	v_add_u32_e32 v240, 15, v240
	v_lshlrev_b32_e32 v213, 2, v240
	v_add_u32_e32 v240, 3, v241
	v_cmp_gt_u32_e64 s[46:47], 16, v240
	v_add_u32_e32 v240, 4, v235
	v_med3_i32 v240, v240, -15, 15
	v_add_u32_e32 v240, 15, v240
	v_lshlrev_b32_e32 v214, 2, v240
	v_add_u32_e32 v240, 4, v241
	v_cmp_gt_u32_e64 s[48:49], 16, v240
	v_add_u32_e32 v240, 5, v235
	v_med3_i32 v240, v240, -15, 15
	v_add_u32_e32 v240, 15, v240
	v_lshlrev_b32_e32 v215, 2, v240
	v_add_u32_e32 v240, 5, v241
	v_cmp_gt_u32_e64 s[50:51], 16, v240
	v_add_u32_e32 v240, 6, v235
	v_med3_i32 v240, v240, -15, 15
	v_add_u32_e32 v240, 15, v240
	v_lshlrev_b32_e32 v216, 2, v240
	v_add_u32_e32 v240, 6, v241
	v_cmp_gt_u32_e64 s[52:53], 16, v240
	v_add_u32_e32 v240, 7, v235
	v_med3_i32 v240, v240, -15, 15
	v_add_u32_e32 v240, 15, v240
	v_lshlrev_b32_e32 v217, 2, v240
	v_add_u32_e32 v240, 7, v241
	v_cmp_gt_u32_e64 s[54:55], 16, v240
	s_waitcnt lgkmcnt(0)
	s_and_b32 s14, s98, 0xff
	s_lshl_b32 s36, s14, 9
	s_add_u32 s7, s7, s36
	s_and_b32 s15, s7, 7
	s_bfe_u32 s16, s7, 0x50003
	s_lshr_b32 s17, s7, 8
	s_sub_i32 s18, s16, 4
	s_max_i32 s18, s18, 0
	s_min_i32 s18, s18, 24
	s_lshl_b32 s19, s17, 11
	s_lshl_b32 s20, s18, 6
	s_add_u32 s20, s20, s19
	s_add_u32 s20, s20, s8
	s_lshl_b32 s21, s16, 6
	s_add_u32 s21, s21, s19
	s_add_u32 s21, s21, s9
	s_lshl_b32 s22, s15, 7
	s_lshl_b32 s23, s20, 10
	s_add_u32 s23, s23, s22
	s_add_u32 s0, s10, 0x5200000
	s_addc_u32 s1, s11, 0
	s_add_u32 s0, s0, s23
	s_addc_u32 s1, s1, 0
	s_lshl_b32 s23, s21, 10
	s_add_u32 s23, s23, s22
	s_add_u32 s2, s10, 0x4200000
	s_addc_u32 s3, s11, 0
	s_add_u32 s2, s2, s23
	s_addc_u32 s3, s3, 0
	global_load_dwordx4 v[0:3], v221, s[2:3]
	global_load_dwordx4 v[4:7], v221, s[2:3] offset:64
	global_load_dwordx4 v[72:75], v218, s[0:1]
	global_load_dwordx4 v[76:79], v218, s[0:1] offset:64
	global_load_dwordx4 v[80:83], v219, s[0:1]
	global_load_dwordx4 v[84:87], v219, s[0:1] offset:64
	s_add_u32 s0, s0, 0x10000
	s_addc_u32 s1, s1, 0
	global_load_dwordx4 v[88:91], v218, s[0:1]
	global_load_dwordx4 v[92:95], v218, s[0:1] offset:64
	global_load_dwordx4 v[96:99], v219, s[0:1]
	global_load_dwordx4 v[100:103], v219, s[0:1] offset:64
	s_add_u32 s0, s0, 0x10000
	s_addc_u32 s1, s1, 0
	global_load_dwordx4 v[104:107], v218, s[0:1]
	global_load_dwordx4 v[108:111], v218, s[0:1] offset:64
	global_load_dwordx4 v[112:115], v219, s[0:1]
	global_load_dwordx4 v[116:119], v219, s[0:1] offset:64
	s_add_u32 s0, s0, 0x10000
	s_addc_u32 s1, s1, 0
	global_load_dwordx4 v[120:123], v218, s[0:1]
	global_load_dwordx4 v[124:127], v218, s[0:1] offset:64
	global_load_dwordx4 v[128:131], v219, s[0:1]
	global_load_dwordx4 v[132:135], v219, s[0:1] offset:64
	s_add_u32 s0, s0, 0x10000
	s_addc_u32 s1, s1, 0
	global_load_dwordx4 v[146:149], v218, s[0:1]
	global_load_dwordx4 v[150:153], v218, s[0:1] offset:64
	global_load_dwordx4 v[154:157], v219, s[0:1]
	global_load_dwordx4 v[158:161], v219, s[0:1] offset:64
	s_add_u32 s0, s0, 0x10000
	s_addc_u32 s1, s1, 0
	global_load_dwordx4 v[162:165], v218, s[0:1]
	global_load_dwordx4 v[166:169], v218, s[0:1] offset:64
	global_load_dwordx4 v[170:173], v219, s[0:1]
	global_load_dwordx4 v[174:177], v219, s[0:1] offset:64
	s_add_u32 s0, s0, 0x10000
	s_addc_u32 s1, s1, 0
